# grid barrier XCD-leader tail: drop the two vmcnt(0) waits around the generation-bump atomic (next barrier entry already drains them)
# speedup vs baseline: 1.0123x; 1.0123x over previous
; DI unsigned xb_ld(unsigned* p) { return __hip_atomic_load(p, __ATOMIC_RELAXED, __HIP_MEMORY_SCOPE_AGENT); }
; DI unsigned xb_add(unsigned* p, unsigned v) { return __hip_atomic_fetch_add(p, v, __ATOMIC_RELAXED, __HIP_MEMORY_SCOPE_AGENT); }
; #define XB_SPIN(cond, bar) do { unsigned _sp = 0; while (cond) { __builtin_amdgcn_s_sleep(1); \
;     if ((++_sp & 255u) == 0u) { if (xb_ld(&(bar)[XB_TMO])) break; if (_sp > XB_SPIN_CAP) { atomicAdd(&(bar)[XB_TMO], 1u); break; } } } } while (0)
; DI void xcd_barrier(const XcdBarrier& b) {
;     ...
;     const unsigned old = xb_add(&bar[XB_XSUB(b.x)], 1u);
;     const unsigned gen = old / nloc;
;     if (old + 1u == (gen + 1u) * nloc) {
;       __builtin_amdgcn_fence(__ATOMIC_RELEASE, "agent");
;       asm volatile("s_waitcnt vmcnt(0)" ::: "memory");
;       const unsigned og = xb_add(&bar[XB_TOP], 1u);
;       const unsigned tg = og / nx;
;       if (og + 1u == (tg + 1u) * nx) xb_add(&bar[XB_TOPGEN], 1u);
;       else XB_SPIN(xb_ld(&bar[XB_TOPGEN]) == tg, bar);
;       __builtin_amdgcn_fence(__ATOMIC_ACQUIRE, "agent");
;       xb_add(&bar[XB_XGEN(b.x)], 1u);
;       asm volatile("s_waitcnt vmcnt(0)" ::: "memory");
; DI void convert_mat(const float* W, int K, int N, const float* g, bf16_t* Wt, int mode, int& off, int vb, int nb, bool f16 = false) {
;   const int ntn = (N + 127) >> 7;
;   const int ntiles = (K >> 6) * ntn;
;   const int first = (int)((vb + nb - (off % nb)) % nb);
;   for (int i = first; i < ntiles; i += nb) convert_tile(W, K, N, g, Wt, mode, i / ntn, i % ntn, f16);
;   off += ntiles;
; }
.LBB0_178:
	s_or_b64 exec, exec, s[2:3]
	s_mov_b64 s[2:3], exec
	v_mbcnt_lo_u32_b32 v0, s2, 0
	v_mbcnt_hi_u32_b32 v0, s3, v0
	v_cmp_eq_u32_e32 vcc, 0, v0
	s_and_saveexec_b64 s[4:5], vcc
	s_cbranch_execz .LBB0_180
	s_bcnt1_i32_b64 s2, s[2:3]
	v_mov_b32_e32 v1, s2
	v_readlane_b32 s2, v253, 21
	v_mov_b32_e32 v0, 0
	v_readlane_b32 s3, v253, 22
	s_nop 4
	global_atomic_add v0, v1, s[2:3]
.LBB0_180:
	s_or_b64 exec, exec, s[4:5]
.LBB0_181:
	s_or_b64 exec, exec, s[0:1]
	s_load_dwordx2 s[6:7], s[70:71], 0xd0
	s_waitcnt lgkmcnt(0)
	v_readlane_b32 s7, v252, 0
	v_mov_b32_e32 v2, 0
	v_mov_b32_e32 v234, 0x21010
	v_mbcnt_hi_u32_b32 v225, -1, v21
	s_cmpk_lt_i32 s6, 0x100
	s_cselect_b64 s[0:1], -1, 0
	v_writelane_b32 v253, s0, 27
	s_cmpk_gt_i32 s7, 0x7f
	v_mov_b32_e32 v235, 0xf149f2ca
	v_writelane_b32 v253, s1, 28
	s_cselect_b64 s[0:1], -1, 0
	v_writelane_b32 v253, s0, 29
	s_add_i32 s4, s6, 0xffffff80
	s_lshl_b32 s8, s4, 9
	v_writelane_b32 v253, s1, 30
	s_add_i32 s1, s7, 0xffffff80
	s_add_i32 s0, s4, s1
	s_lshl_b32 s1, s1, 9
	v_writelane_b32 v253, s1, 31
	v_readlane_b32 s1, v252, 12
	s_cmpk_lt_i32 s1, 0x100
	v_cvt_f32_u32_e32 v0, s4
	s_cselect_b64 s[2:3], -1, 0
	s_lshl_b32 s10, s6, 9
	v_writelane_b32 v253, s2, 32
	s_cmpk_lt_i32 s7, 0x2c0
	v_rcp_iflag_f32_e32 v0, v0
	v_writelane_b32 v253, s3, 33
	s_cselect_b64 s[2:3], -1, 0
	v_writelane_b32 v253, s2, 34
	s_cmpk_lt_i32 s7, 0x200
	v_mul_f32_e32 v0, 0x4f7ffffe, v0
	v_writelane_b32 v253, s3, 35
	s_cselect_b64 s[2:3], -1, 0
	v_writelane_b32 v253, s2, 36
	s_cmpk_lt_i32 s7, 0x100
	v_cvt_u32_f32_e32 v0, v0
	v_writelane_b32 v253, s3, 37
	s_cselect_b64 s[2:3], -1, 0
	v_writelane_b32 v253, s2, 38
	s_cmpk_lt_i32 s7, 0xa0
	s_mov_b32 s17, 0xefa18f08
	v_writelane_b32 v253, s3, 39
	s_cselect_b64 s[2:3], -1, 0
	v_writelane_b32 v253, s2, 40
	s_cmpk_lt_i32 s7, 0x600
	s_mov_b64 s[34:35], 0x40080
	v_writelane_b32 v253, s3, 41
	s_cselect_b64 s[2:3], -1, 0
	v_writelane_b32 v253, s2, 42
	s_sub_i32 s1, 0x80, s6
	s_mov_b64 s[18:19], 0x40100
	v_writelane_b32 v253, s3, 43
	v_readfirstlane_b32 s2, v0
	s_mul_i32 s3, s1, s2
	s_mul_hi_u32 s3, s2, s3
	s_add_i32 s2, s2, s3
	s_mul_hi_u32 s2, s0, s2
	s_mul_i32 s2, s2, s4
	s_sub_i32 s2, s0, s2
	s_sub_i32 s3, s2, s4
	s_cmp_ge_u32 s2, s4
	s_cselect_b32 s2, s3, s2
	s_sub_i32 s3, s2, s4
	s_cmp_ge_u32 s2, s4
	s_cselect_b32 s2, s3, s2
	s_cmpk_lt_u32 s2, 0x100
	v_writelane_b32 v253, s2, 44
	s_cselect_b64 s[2:3], -1, 0
	s_max_i32 s1, s4, s1
	v_cvt_f32_u32_e32 v0, s1
	v_writelane_b32 v253, s2, 45
	s_mov_b64 s[22:23], 0x180
	s_mov_b32 s28, 0x3e16c740
	v_rcp_iflag_f32_e32 v0, v0
	v_writelane_b32 v253, s3, 46
	s_sub_i32 s2, 0, s1
	v_writelane_b32 v253, s4, 47
	v_mul_f32_e32 v0, 0x4f7ffffe, v0
	v_cvt_u32_f32_e32 v0, v0
	s_mov_b32 s16, 0x3e38aa3b
	s_mov_b32 s26, 0x3e0293ee
	v_readfirstlane_b32 s3, v0
	s_mul_i32 s2, s2, s3
	s_mul_hi_u32 s2, s3, s2
	s_add_i32 s3, s3, s2
	s_lshr_b32 s2, s3, 24
	s_mul_i32 s2, s2, s1
	s_sub_i32 s2, 0x100, s2
	s_sub_i32 s4, s2, s1
	s_cmp_ge_u32 s2, s1
	s_cselect_b32 s2, s4, s2
	s_sub_i32 s4, s2, s1
	s_cmp_ge_u32 s2, s1
	s_cselect_b32 s2, s4, s2
	s_sub_i32 s2, s0, s2
	s_ashr_i32 s4, s2, 31
	s_abs_i32 s2, s2
	s_mul_hi_u32 s5, s2, s3
	s_mul_i32 s5, s5, s1
	s_sub_i32 s2, s2, s5
	s_sub_i32 s5, s2, s1
	s_cmp_ge_u32 s2, s1
	s_cselect_b32 s2, s5, s2
	s_sub_i32 s5, s2, s1
	s_cmp_ge_u32 s2, s1
	s_cselect_b32 s2, s5, s2
	s_xor_b32 s2, s2, s4
	s_sub_i32 s2, s2, s4
	v_writelane_b32 v253, s2, 48
	s_cmp_lt_i32 s2, 24
	s_mul_hi_u32 s2, s3, 0x118
	s_cselect_b64 s[4:5], -1, 0
	s_mul_i32 s2, s2, s1
	v_writelane_b32 v253, s4, 49
	s_sub_i32 s2, 0x118, s2
	s_barrier
	v_writelane_b32 v253, s5, 50
	s_sub_i32 s4, s2, s1
	s_cmp_ge_u32 s2, s1
	s_cselect_b32 s2, s4, s2
	s_sub_i32 s4, s2, s1
	s_cmp_ge_u32 s2, s1
	s_cselect_b32 s2, s4, s2
	s_sub_i32 s2, s0, s2
	s_ashr_i32 s4, s2, 31
	s_abs_i32 s2, s2
	s_mul_hi_u32 s5, s2, s3
	s_mul_i32 s5, s5, s1
	s_sub_i32 s2, s2, s5
	s_sub_i32 s5, s2, s1
	s_cmp_ge_u32 s2, s1
	s_cselect_b32 s2, s5, s2
	s_sub_i32 s5, s2, s1
	s_cmp_ge_u32 s2, s1
	s_cselect_b32 s2, s5, s2
	s_xor_b32 s2, s2, s4
	s_sub_i32 s2, s2, s4
	v_writelane_b32 v253, s2, 51
	s_cmp_lt_i32 s2, 16
	s_mul_hi_u32 s2, s3, 0x128
	s_cselect_b64 s[4:5], -1, 0
	s_mul_i32 s2, s2, s1
	v_writelane_b32 v253, s4, 52
	s_sub_i32 s2, 0x128, s2
	s_nop 0
	v_writelane_b32 v253, s5, 53
	s_sub_i32 s4, s2, s1
	s_cmp_ge_u32 s2, s1
	s_cselect_b32 s2, s4, s2
	s_sub_i32 s4, s2, s1
	s_cmp_ge_u32 s2, s1
	s_cselect_b32 s2, s4, s2
	s_sub_i32 s2, s0, s2
	s_ashr_i32 s4, s2, 31
	s_abs_i32 s2, s2
	s_mul_hi_u32 s5, s2, s3
	s_mul_i32 s5, s5, s1
	s_sub_i32 s2, s2, s5
	s_sub_i32 s5, s2, s1
	s_cmp_ge_u32 s2, s1
	s_cselect_b32 s2, s5, s2
	s_sub_i32 s5, s2, s1
	s_cmp_ge_u32 s2, s1
	s_cselect_b32 s2, s5, s2
	s_xor_b32 s2, s2, s4
	s_sub_i32 s2, s2, s4
	v_writelane_b32 v253, s2, 54
	s_cmpk_lt_i32 s2, 0x80
	s_mul_hi_u32 s2, s3, 0x1a8
	s_cselect_b64 s[4:5], -1, 0
	s_mul_i32 s2, s2, s1
	v_writelane_b32 v253, s4, 55
	s_sub_i32 s2, 0x1a8, s2
	s_nop 0
	v_writelane_b32 v253, s5, 56
	s_sub_i32 s4, s2, s1
	s_cmp_ge_u32 s2, s1
	s_cselect_b32 s2, s4, s2
	s_sub_i32 s4, s2, s1
	s_cmp_ge_u32 s2, s1
	s_cselect_b32 s2, s4, s2
	s_sub_i32 s2, s0, s2
	s_ashr_i32 s4, s2, 31
	s_abs_i32 s2, s2
	s_mul_hi_u32 s5, s2, s3
	s_mul_i32 s5, s5, s1
	s_sub_i32 s2, s2, s5
	s_sub_i32 s5, s2, s1
	s_cmp_ge_u32 s2, s1
	s_cselect_b32 s2, s5, s2
	s_sub_i32 s5, s2, s1
	s_cmp_ge_u32 s2, s1
	s_cselect_b32 s2, s5, s2
	s_xor_b32 s2, s2, s4
	s_sub_i32 s2, s2, s4
	v_writelane_b32 v253, s2, 57
	s_cmp_lt_i32 s2, 64
	s_mul_hi_u32 s2, s3, 0x1e8
	s_cselect_b64 s[4:5], -1, 0
	s_mul_i32 s2, s2, s1
	v_writelane_b32 v253, s4, 58
	s_sub_i32 s2, 0x1e8, s2
	s_nop 0
	v_writelane_b32 v253, s5, 59
; #define GSYNC() do { for (int _r = 0; _r < REP_SYNC; ++_r) xcd_barrier(xbar); } while (0)
; DI unsigned char* wsp() { return (unsigned char*)inp(25); }
; DI int tid_opaque() { int t = threadIdx.x; asm volatile("" : "+v"(t)); return t; }
; DI void convert_mat(const float* W, int K, int N, const float* g, bf16_t* Wt, int mode, int& off, int vb, int nb, bool f16 = false) {
;   const int ntn = (N + 127) >> 7;
;   const int ntiles = (K >> 6) * ntn;
;   const int first = (int)((vb + nb - (off % nb)) % nb);
;   for (int i = first; i < ntiles; i += nb) convert_tile(W, K, N, g, Wt, mode, i / ntn, i % ntn, f16);
;   off += ntiles;
; }
; DI void convert_layer(int L, int vb, int vnb) {
;   bf16_t* wb = (bf16_t*)(wsp() + OFF_W) + (size_t)(L & 1) * WSZ;
;   const int j = L >> 1;
;   int off = 0;
;   if ((L & 1) == 0) {
;     convert_mat(inp(3) + (size_t)j * 1024 * 1536, 1024, 1536, inp(2) + L * 1024, wb + W_IN, 0, off, vb, vnb, true);
;     convert_mat(inp(7) + (size_t)j * 1024 * 1024, 1024, 1024, nullptr, wb + W_OUT, 0, off, vb, vnb);
;   } else {
;     convert_mat(inp(8) + (size_t)j * 1024 * 1952, 1024, 1952, inp(2) + L * 1024, wb + W_IN, 1, off, vb, vnb, true);
;     convert_mat(inp(11) + (size_t)j * 256 * 768, 256, 768, inp(9) + j * 256, wb + W_UQ, 0, off, vb, vnb);
;     convert_mat(inp(12) + (size_t)j * 128 * 1024, 128, 1024, inp(10) + j * 128, wb + W_UKV, 0, off, vb, vnb);
;     convert_mat(inp(14) + (size_t)j * 1024 * 1024, 1024, 1024, nullptr, wb + W_OUT, 0, off, vb, vnb);
;     unsigned zz = 0u;
;     asm volatile("" : "+v"(zz));
;     uint4 z4 = {zz, zz, zz, zz};
;     uint4* zp = (uint4*)(wb + W_IN + (size_t)416 * 1024);
;     for (int i = vb * NT + tid_opaque(); i < 96 * 1024 / 8; i += vnb * NT) zp[i] = z4;
;   }
;   convert_mat(inp(17) + (size_t)L * 1024 * 512, 1024, 512, inp(15) + L * 1024, wb + W_XQ, 0, off, vb, vnb, true);
;   convert_mat(inp(18) + (size_t)L * 1024 * 1024, 1024, 1024, inp(16) + L * 1024, wb + W_XKV, 0, off, vb, vnb);
;   convert_mat(inp(19) + (size_t)L * 512 * 1024, 512, 1024, nullptr, wb + W_XO, 0, off, vb, vnb);
;   convert_mat(inp(21) + (size_t)L * 1024 * 5632, 1024, 5632, inp(20) + L * 1024, wb + W_GU, 2, off, vb, vnb, true);
;   convert_mat(inp(22) + (size_t)L * 2816 * 1024, 2816, 1024, nullptr, wb + W_DOWN, 0, off, vb, vnb);
; __global__ void __launch_bounds__(512, 2) mega(Params p) {
;     ...
;     GSYNC();
;   }
	s_sub_i32 s4, s2, s1
	s_cmp_ge_u32 s2, s1
	s_cselect_b32 s2, s4, s2
	s_sub_i32 s4, s2, s1
	s_cmp_ge_u32 s2, s1
	s_cselect_b32 s2, s4, s2
	s_sub_i32 s2, s0, s2
	s_ashr_i32 s4, s2, 31
	s_abs_i32 s2, s2
	s_mul_hi_u32 s5, s2, s3
	s_mul_i32 s5, s5, s1
	s_sub_i32 s2, s2, s5
	s_sub_i32 s5, s2, s1
	s_cmp_ge_u32 s2, s1
	s_cselect_b32 s2, s5, s2
	s_sub_i32 s5, s2, s1
	s_cmp_ge_u32 s2, s1
	s_cselect_b32 s2, s5, s2
	s_xor_b32 s2, s2, s4
	s_sub_i32 s2, s2, s4
	v_writelane_b32 v253, s2, 60
	s_cmpk_lt_i32 s2, 0x80
	s_mul_hi_u32 s2, s3, 0x268
	s_cselect_b64 s[4:5], -1, 0
	s_mul_i32 s2, s2, s1
	v_writelane_b32 v253, s4, 61
	s_sub_i32 s2, 0x268, s2
	s_nop 0
	v_writelane_b32 v253, s5, 62
	s_sub_i32 s4, s2, s1
	s_cmp_ge_u32 s2, s1
	s_cselect_b32 s2, s4, s2
	s_sub_i32 s4, s2, s1
	s_cmp_ge_u32 s2, s1
	s_cselect_b32 s2, s4, s2
	s_sub_i32 s2, s0, s2
	s_ashr_i32 s4, s2, 31
	s_abs_i32 s2, s2
	s_mul_hi_u32 s5, s2, s3
	s_mul_i32 s5, s5, s1
	s_sub_i32 s2, s2, s5
	s_sub_i32 s5, s2, s1
	s_cmp_ge_u32 s2, s1
	s_cselect_b32 s2, s5, s2
	s_sub_i32 s5, s2, s1
	s_cmp_ge_u32 s2, s1
	s_cselect_b32 s2, s5, s2
	s_xor_b32 s2, s2, s4
	s_sub_i32 s2, s2, s4
	v_writelane_b32 v253, s2, 63
	s_cmp_lt_i32 s2, 64
	s_mul_hi_u32 s2, s3, 0x2a8
	s_cselect_b64 s[4:5], -1, 0
	s_mul_i32 s2, s2, s1
	v_writelane_b32 v254, s4, 0
	s_sub_i32 s2, 0x2a8, s2
	s_nop 0
	v_writelane_b32 v254, s5, 1
	s_sub_i32 s4, s2, s1
	s_cmp_ge_u32 s2, s1
	s_cselect_b32 s2, s4, s2
	s_sub_i32 s4, s2, s1
	s_cmp_ge_u32 s2, s1
	s_cselect_b32 s2, s4, s2
	s_sub_i32 s2, s0, s2
	s_ashr_i32 s4, s2, 31
	s_abs_i32 s2, s2
	s_mul_hi_u32 s5, s2, s3
	s_mul_i32 s5, s5, s1
	s_sub_i32 s2, s2, s5
	s_sub_i32 s5, s2, s1
	s_cmp_ge_u32 s2, s1
	s_cselect_b32 s2, s5, s2
	s_sub_i32 s5, s2, s1
	s_cmp_ge_u32 s2, s1
	s_cselect_b32 s2, s5, s2
	s_xor_b32 s2, s2, s4
	s_sub_i32 s2, s2, s4
	v_writelane_b32 v254, s2, 2
	s_cmpk_lt_i32 s2, 0x2c0
	s_mul_hi_u32 s2, s3, 0x568
	s_cselect_b64 s[4:5], -1, 0
	s_mul_i32 s2, s2, s1
	v_writelane_b32 v254, s4, 3
	s_sub_i32 s2, 0x568, s2
	s_nop 0
	v_writelane_b32 v254, s5, 4
	s_sub_i32 s4, s2, s1
	s_cmp_ge_u32 s2, s1
	s_cselect_b32 s2, s4, s2
	s_sub_i32 s4, s2, s1
	s_cmp_ge_u32 s2, s1
	s_cselect_b32 s2, s4, s2
	s_sub_i32 s0, s0, s2
	s_ashr_i32 s2, s0, 31
	s_abs_i32 s0, s0
	s_mul_hi_u32 s3, s0, s3
	s_mul_i32 s3, s3, s1
	s_sub_i32 s0, s0, s3
	s_sub_i32 s3, s0, s1
	s_cmp_ge_u32 s0, s1
	s_cselect_b32 s0, s3, s0
	s_sub_i32 s3, s0, s1
	s_cmp_ge_u32 s0, s1
	s_cselect_b32 s0, s3, s0
	s_xor_b32 s0, s0, s2
	s_sub_i32 s0, s0, s2
	s_cmpk_lt_i32 s0, 0x160
	v_writelane_b32 v254, s0, 5
	s_cselect_b64 s[0:1], -1, 0
	v_writelane_b32 v254, s0, 6
	v_readlane_b32 s5, v252, 8
	v_readlane_b32 s3, v252, 9
	v_writelane_b32 v254, s1, 7
	s_lshr_b32 s0, s5, 24
	s_mul_i32 s0, s0, s3
	s_sub_i32 s0, 0x100, s0
	s_sub_i32 s1, s0, s3
	s_cmp_ge_u32 s0, s3
	s_cselect_b32 s0, s1, s0
	s_sub_i32 s1, s0, s3
	s_cmp_ge_u32 s0, s3
	s_cselect_b32 s0, s1, s0
	v_readlane_b32 s4, v252, 7
	s_sub_i32 s0, s4, s0
	s_ashr_i32 s1, s0, 31
	s_abs_i32 s0, s0
	s_mul_hi_u32 s2, s0, s5
	s_mul_i32 s2, s2, s3
	s_sub_i32 s0, s0, s2
	s_sub_i32 s2, s0, s3
	s_cmp_ge_u32 s0, s3
	s_cselect_b32 s0, s2, s0
	s_sub_i32 s2, s0, s3
	s_cmp_ge_u32 s0, s3
	s_cselect_b32 s0, s2, s0
	s_xor_b32 s0, s0, s1
	s_sub_i32 s0, s0, s1
	s_cmp_lt_i32 s0, 24
	v_writelane_b32 v254, s0, 8
	s_cselect_b64 s[0:1], -1, 0
	v_writelane_b32 v254, s0, 9
	s_nop 1
	v_writelane_b32 v254, s1, 10
	s_mul_hi_u32 s0, s5, 0x118
	s_mul_i32 s0, s0, s3
	s_sub_i32 s0, 0x118, s0
	s_sub_i32 s1, s0, s3
	s_cmp_ge_u32 s0, s3
	s_cselect_b32 s0, s1, s0
	s_sub_i32 s1, s0, s3
	s_cmp_ge_u32 s0, s3
	s_cselect_b32 s0, s1, s0
	s_sub_i32 s0, s4, s0
	s_ashr_i32 s1, s0, 31
	s_abs_i32 s0, s0
	s_mul_hi_u32 s2, s0, s5
	s_mul_i32 s2, s2, s3
	s_sub_i32 s0, s0, s2
	s_sub_i32 s2, s0, s3
	s_cmp_ge_u32 s0, s3
	s_cselect_b32 s0, s2, s0
	s_sub_i32 s2, s0, s3
	s_cmp_ge_u32 s0, s3
	s_cselect_b32 s0, s2, s0
	s_xor_b32 s0, s0, s1
	s_sub_i32 s0, s0, s1
	s_cmp_lt_i32 s0, 16
	v_writelane_b32 v254, s0, 11
	s_cselect_b64 s[0:1], -1, 0
	v_writelane_b32 v254, s0, 12
	s_nop 1
	v_writelane_b32 v254, s1, 13
	s_mul_hi_u32 s0, s5, 0x128
	s_mul_i32 s0, s0, s3
	s_sub_i32 s0, 0x128, s0
	s_sub_i32 s1, s0, s3
	s_cmp_ge_u32 s0, s3
	s_cselect_b32 s0, s1, s0
	s_sub_i32 s1, s0, s3
	s_cmp_ge_u32 s0, s3
	s_cselect_b32 s0, s1, s0
	s_sub_i32 s0, s4, s0
	s_ashr_i32 s1, s0, 31
	s_abs_i32 s0, s0
	s_mul_hi_u32 s2, s0, s5
	s_mul_i32 s2, s2, s3
	s_sub_i32 s0, s0, s2
	s_sub_i32 s2, s0, s3
	s_cmp_ge_u32 s0, s3
	s_cselect_b32 s0, s2, s0
	s_sub_i32 s2, s0, s3
	s_cmp_ge_u32 s0, s3
	s_cselect_b32 s0, s2, s0
	s_xor_b32 s0, s0, s1
	s_sub_i32 s0, s0, s1
	s_cmpk_lt_i32 s0, 0x80
	v_writelane_b32 v254, s0, 14
	s_cselect_b64 s[0:1], -1, 0
	v_writelane_b32 v254, s0, 15
	s_ashr_i32 s9, s8, 31
	s_lshl_b64 s[2:3], s[8:9], 4
	v_writelane_b32 v254, s1, 16
	s_lshl_b32 s0, s7, 2
	v_writelane_b32 v254, s0, 17
	s_lshl_b32 s0, s6, 2
	v_writelane_b32 v254, s0, 18
	s_lshl_b32 s0, s7, 8
	v_writelane_b32 v254, s0, 19
	s_lshl_b32 s0, s6, 8
	v_writelane_b32 v254, s0, 20
	s_lshl_b32 s0, s7, 1
	v_writelane_b32 v254, s0, 21
	s_lshl_b32 s0, s6, 1
	v_writelane_b32 v254, s0, 22
	s_lshl_b32 s0, s7, 5
	v_writelane_b32 v254, s0, 23
	s_lshl_b32 s0, s6, 5
	v_writelane_b32 v254, s0, 24
	s_mov_b32 s1, 0
	s_mov_b32 s0, s8
	v_writelane_b32 v254, s0, 25
	s_ashr_i32 s11, s10, 31
	s_mov_b64 s[8:9], 0
	v_writelane_b32 v254, s1, 26
	v_writelane_b32 v254, s2, 27
	s_mov_b32 s0, s10
	s_nop 0
	v_writelane_b32 v254, s3, 28
	v_writelane_b32 v254, s0, 29
	s_lshl_b64 s[2:3], s[10:11], 4
	s_mov_b64 s[10:11], 0x100
	v_writelane_b32 v254, s1, 30
	v_writelane_b32 v254, s2, 31
	s_mov_b32 s0, 0
	s_nop 0
	v_writelane_b32 v254, s3, 32
	s_mov_b64 s[2:3], -1
	v_writelane_b32 v254, s2, 33
	s_nop 1
	v_writelane_b32 v254, s3, 34
	v_writelane_b32 v254, s0, 35
	s_nop 1
	v_writelane_b32 v254, s1, 36
	v_writelane_b32 v254, s2, 37
	v_writelane_b32 v254, s3, 38
	v_writelane_b32 v254, s70, 39
	s_nop 1
	v_writelane_b32 v254, s71, 40
	s_branch .LBB0_184
.LBB0_182:
	s_or_b64 exec, exec, s[4:5]
.LBB0_183:
	s_or_b64 exec, exec, s[0:1]
	v_readlane_b32 s2, v254, 33
	v_readlane_b32 s8, v254, 46
	v_readlane_b32 s3, v254, 34
	v_readlane_b32 s1, v254, 41
	v_readlane_b32 s9, v254, 47
	s_xor_b64 s[2:3], s[2:3], -1
	s_add_i32 s1, s1, 1
	s_xor_b64 s[8:9], s[8:9], -1
	v_writelane_b32 v254, s2, 33
	s_cmp_eq_u32 s1, 4
	s_waitcnt lgkmcnt(0)
	v_writelane_b32 v254, s3, 34
	s_barrier
	s_cbranch_scc0 .LBB0_184
	s_getpc_b64 s[98:99]

; #define GSYNC() do { for (int _r = 0; _r < REP_SYNC; ++_r) xcd_barrier(xbar); } while (0)
; DI unsigned xb_ld(unsigned* p) { return __hip_atomic_load(p, __ATOMIC_RELAXED, __HIP_MEMORY_SCOPE_AGENT); }
; DI unsigned xb_add(unsigned* p, unsigned v) { return __hip_atomic_fetch_add(p, v, __ATOMIC_RELAXED, __HIP_MEMORY_SCOPE_AGENT); }
; #define XB_SPIN(cond, bar) do { unsigned _sp = 0; while (cond) { __builtin_amdgcn_s_sleep(1); \
;     if ((++_sp & 255u) == 0u) { if (xb_ld(&(bar)[XB_TMO])) break; if (_sp > XB_SPIN_CAP) { atomicAdd(&(bar)[XB_TMO], 1u); break; } } } } while (0)
; #define G_SSCQ ((float*)(wsp() + OFF_SSCQ))
; #define G_SSCKV ((float*)(wsp() + OFF_SSCKV))
; DI void xcd_barrier(const XcdBarrier& b) {
;     ...
;       xb_add(&bar[XB_XGEN(b.x)], 1u);
;       asm volatile("s_waitcnt vmcnt(0)" ::: "memory");
;     } else {
;       XB_SPIN(xb_ld(&bar[XB_XGEN(b.x)]) == gen, bar);
;       __builtin_amdgcn_fence(__ATOMIC_ACQUIRE, "agent");
;       asm volatile("s_waitcnt vmcnt(0)" ::: "memory");
;     }
;   }
;   __syncthreads();
; __global__ void __launch_bounds__(512, 2) mega(Params p) {
;     ...
;     GSYNC();
;     if (odd) {
;       const int total = 3 * 64 + 8 * 64;
;       for (int rp = 0; rp < REP_P1; ++rp)
;       for (int item = bid; item < total; item += nb) {
;         if (item < 192) {
;           const int nt = item >> 6, mt = item & 63;
;           e.ss = G_SSCQ; e.nss = 4; e.inv_n = 1.f / 256.f; e.out = G_QC; e.ldo = 768;
;           gemm_tile<EPI_UQ, 256, false>(G_ZB, ZLD, wb + W_UQ, 256, mt * 256, nt * 256, e);
;         } else {
;           const int it = item - 192;
;           const int nt = it >> 6, mt = it & 63;
;           e.ss = G_SSCKV; e.nss = 2; e.inv_n = 1.f / 128.f; e.out = G_KVC; e.ldo = 1024;
;           gemm_tile<EPI_PLAIN, 128, false>(G_ZB + 256, ZLD, wb + W_UKV, 128, mt * 256, nt * 128, e);
.LBB0_539:
	s_or_b64 exec, exec, s[2:3]
	s_mov_b64 s[2:3], exec
	v_mbcnt_lo_u32_b32 v0, s2, 0
	v_mbcnt_hi_u32_b32 v0, s3, v0
	v_cmp_eq_u32_e32 vcc, 0, v0
	s_and_saveexec_b64 s[4:5], vcc
	s_cbranch_execz .LBB0_541
	s_bcnt1_i32_b64 s2, s[2:3]
	v_mov_b32_e32 v0, s2
	v_readlane_b32 s2, v253, 21
	v_readlane_b32 s3, v253, 22
	s_nop 4
	global_atomic_add v2, v0, s[2:3]
.LBB0_541:
	s_or_b64 exec, exec, s[4:5]
.LBB0_542:
	s_or_b64 exec, exec, s[0:1]
	s_and_b64 vcc, exec, s[38:39]
	s_waitcnt lgkmcnt(0)
	s_barrier
	s_cbranch_vccz .LBB0_631
	v_readlane_b32 s0, v253, 34
	v_readlane_b32 s1, v253, 35
	s_andn2_b64 vcc, exec, s[0:1]
	s_cbranch_vccnz .LBB0_578
	v_readlane_b32 s0, v254, 44
	s_add_u32 s4, s0, 0x460000
	v_readlane_b32 s1, v254, 45
	s_addc_u32 s5, s1, 0
	s_add_u32 s7, s0, 0x400000
	s_addc_u32 s20, s1, 0
	v_readlane_b32 s21, v254, 17
	v_readlane_b32 s24, v254, 21
	v_readlane_b32 s25, v254, 19
	v_readlane_b32 s33, v252, 0
	s_branch .LBB0_547

; DI unsigned xb_ld(unsigned* p) { return __hip_atomic_load(p, __ATOMIC_RELAXED, __HIP_MEMORY_SCOPE_AGENT); }
; DI unsigned xb_add(unsigned* p, unsigned v) { return __hip_atomic_fetch_add(p, v, __ATOMIC_RELAXED, __HIP_MEMORY_SCOPE_AGENT); }
; #define XB_SPIN(cond, bar) do { unsigned _sp = 0; while (cond) { __builtin_amdgcn_s_sleep(1); \
;     if ((++_sp & 255u) == 0u) { if (xb_ld(&(bar)[XB_TMO])) break; if (_sp > XB_SPIN_CAP) { atomicAdd(&(bar)[XB_TMO], 1u); break; } } } } while (0)
; DI void xcd_barrier(const XcdBarrier& b) {
;     ...
;       xb_add(&bar[XB_XGEN(b.x)], 1u);
;       asm volatile("s_waitcnt vmcnt(0)" ::: "memory");
;     } else {
;       XB_SPIN(xb_ld(&bar[XB_XGEN(b.x)]) == gen, bar);
;       __builtin_amdgcn_fence(__ATOMIC_ACQUIRE, "agent");
;       asm volatile("s_waitcnt vmcnt(0)" ::: "memory");
;     }
;   }
;   __syncthreads();
.LBB0_629:
	s_or_b64 exec, exec, s[4:5]
.LBB0_630:
	s_or_b64 exec, exec, s[0:1]
	s_waitcnt lgkmcnt(0)
	s_barrier

; #define GSYNC() do { for (int _r = 0; _r < REP_SYNC; ++_r) xcd_barrier(xbar); } while (0)
; DI unsigned xb_ld(unsigned* p) { return __hip_atomic_load(p, __ATOMIC_RELAXED, __HIP_MEMORY_SCOPE_AGENT); }
; DI unsigned xb_add(unsigned* p, unsigned v) { return __hip_atomic_fetch_add(p, v, __ATOMIC_RELAXED, __HIP_MEMORY_SCOPE_AGENT); }
; #define XB_SPIN(cond, bar) do { unsigned _sp = 0; while (cond) { __builtin_amdgcn_s_sleep(1); \
;     if ((++_sp & 255u) == 0u) { if (xb_ld(&(bar)[XB_TMO])) break; if (_sp > XB_SPIN_CAP) { atomicAdd(&(bar)[XB_TMO], 1u); break; } } } } while (0)
; #define G_XF (outp())
; #define G_SS ((float*)(wsp() + OFF_SS))
; DI void xcd_barrier(const XcdBarrier& b) {
;     ...
;       xb_add(&bar[XB_XGEN(b.x)], 1u);
;       asm volatile("s_waitcnt vmcnt(0)" ::: "memory");
;     } else {
;       XB_SPIN(xb_ld(&bar[XB_XGEN(b.x)]) == gen, bar);
;       __builtin_amdgcn_fence(__ATOMIC_ACQUIRE, "agent");
;       asm volatile("s_waitcnt vmcnt(0)" ::: "memory");
;     }
;   }
;   __syncthreads();
; __global__ void __launch_bounds__(512, 2) mega(Params p) {
;     ...
;     GSYNC();
;     for (int item = bid; item < 4 * 64; item += nb) {
;       const int nt = item >> 6, mt = item & 63;
;       e.ss = nullptr; e.xf = G_XF; e.xb = G_XB; e.ss_out = G_SS;
;       gemm_tile<EPI_RESID, 256, false>(G_OB, DM, wb + W_OUT, DM, mt * 256, nt * 256, e);
.LBB0_901:
	s_or_b64 exec, exec, s[4:5]
.LBB0_902:
	s_or_b64 exec, exec, s[0:1]
	v_readlane_b32 s0, v253, 38
	v_readlane_b32 s1, v253, 39
	s_and_b64 vcc, exec, s[0:1]
	s_waitcnt lgkmcnt(0)
	s_barrier
	s_cbranch_vccz .LBB0_945
	v_readlane_b32 s0, v254, 44
	s_add_u32 s14, s0, 0x4a0000
	v_readlane_b32 s0, v254, 45
	s_addc_u32 s15, s0, 0
	v_readlane_b32 s0, v254, 42
	v_readlane_b32 s2, v254, 48
	v_readlane_b32 s1, v254, 43
	s_add_u32 s4, s0, s2
	s_addc_u32 s5, s1, 0
	v_readlane_b32 s20, v254, 19
	v_readlane_b32 s21, v254, 17
	v_readlane_b32 s24, v252, 0
	s_branch .LBB0_905

; #define GSYNC() do { for (int _r = 0; _r < REP_SYNC; ++_r) xcd_barrier(xbar); } while (0)
; DI unsigned xb_ld(unsigned* p) { return __hip_atomic_load(p, __ATOMIC_RELAXED, __HIP_MEMORY_SCOPE_AGENT); }
; DI unsigned xb_add(unsigned* p, unsigned v) { return __hip_atomic_fetch_add(p, v, __ATOMIC_RELAXED, __HIP_MEMORY_SCOPE_AGENT); }
; #define XB_SPIN(cond, bar) do { unsigned _sp = 0; while (cond) { __builtin_amdgcn_s_sleep(1); \
;     if ((++_sp & 255u) == 0u) { if (xb_ld(&(bar)[XB_TMO])) break; if (_sp > XB_SPIN_CAP) { atomicAdd(&(bar)[XB_TMO], 1u); break; } } } } while (0)
; #define G_SS ((float*)(wsp() + OFF_SS))
; #define G_SSMEM ((float*)(wsp() + OFF_SSMEM))
; DI void xcd_barrier(const XcdBarrier& b) {
;     ...
;       xb_add(&bar[XB_XGEN(b.x)], 1u);
;       asm volatile("s_waitcnt vmcnt(0)" ::: "memory");
;     } else {
;       XB_SPIN(xb_ld(&bar[XB_XGEN(b.x)]) == gen, bar);
;       __builtin_amdgcn_fence(__ATOMIC_ACQUIRE, "agent");
;       asm volatile("s_waitcnt vmcnt(0)" ::: "memory");
;     }
;   }
;   __syncthreads();
; __global__ void __launch_bounds__(512, 2) mega(Params p) {
;     ...
;     GSYNC();
;     for (int rp = 0; rp < REP_P4; ++rp)
;     for (int item = bid; item < 2 * 64 + 4 * 8; item += nb) {
;       if (item < 128) {
;         const int nt = item >> 6, mt = item & 63;
;         e.ss = G_SS; e.nss = 16; e.inv_n = 1.f / 1024.f; e.out = G_XQ; e.ldo = 512;
;         gemm_tile<EPI_PLAIN, 256, true>(G_XB, DM, wb + W_XQ, DM, mt * 256, nt * 256, e);
;       } else {
;         const int it = item - 128;
;         const int nt = it >> 3, mt = it & 7;
;         e.ss = G_SSMEM; e.nss = 1; e.inv_n = 1.f / 1024.f; e.out = G_MEMKV; e.ldo = 1024;
;         gemm_tile<EPI_PLAIN, 256, false>(G_MEMB, DM, wb + W_XKV, DM, mt * 256, nt * 256, e);
.LBB0_996:
	s_or_b64 exec, exec, s[4:5]
.LBB0_997:
	s_or_b64 exec, exec, s[0:1]
	v_readlane_b32 s0, v253, 40
	v_readlane_b32 s1, v253, 41
	s_andn2_b64 vcc, exec, s[0:1]
	s_waitcnt lgkmcnt(0)
	s_barrier
	s_cbranch_vccnz .LBB0_1020
	v_readlane_b32 s0, v254, 44
	s_add_u32 s24, s0, 0x7a0000
	v_readlane_b32 s1, v254, 45
	s_addc_u32 s25, s1, 0
	s_add_u32 s30, s0, 0x6a0000
	s_addc_u32 s31, s1, 0
	v_readlane_b32 s0, v254, 42
	v_readlane_b32 s2, v254, 48
	v_readlane_b32 s1, v254, 43
	s_add_u32 s4, s0, s2
	s_addc_u32 s5, s1, 0
	v_readlane_b32 s33, v254, 17
	v_readlane_b32 s36, v254, 23
	v_readlane_b32 s37, v254, 19
	v_readlane_b32 s38, v252, 0
	s_branch .LBB0_1001

; #define GSYNC() do { for (int _r = 0; _r < REP_SYNC; ++_r) xcd_barrier(xbar); } while (0)
; DI unsigned xb_ld(unsigned* p) { return __hip_atomic_load(p, __ATOMIC_RELAXED, __HIP_MEMORY_SCOPE_AGENT); }
; DI unsigned xb_add(unsigned* p, unsigned v) { return __hip_atomic_fetch_add(p, v, __ATOMIC_RELAXED, __HIP_MEMORY_SCOPE_AGENT); }
; #define XB_SPIN(cond, bar) do { unsigned _sp = 0; while (cond) { __builtin_amdgcn_s_sleep(1); \
;     if ((++_sp & 255u) == 0u) { if (xb_ld(&(bar)[XB_TMO])) break; if (_sp > XB_SPIN_CAP) { atomicAdd(&(bar)[XB_TMO], 1u); break; } } } } while (0)
; DI void xcd_barrier(const XcdBarrier& b) {
;     ...
;       xb_add(&bar[XB_XGEN(b.x)], 1u);
;       asm volatile("s_waitcnt vmcnt(0)" ::: "memory");
;     } else {
;       XB_SPIN(xb_ld(&bar[XB_XGEN(b.x)]) == gen, bar);
;       __builtin_amdgcn_fence(__ATOMIC_ACQUIRE, "agent");
;       asm volatile("s_waitcnt vmcnt(0)" ::: "memory");
;     }
;   }
;   __syncthreads();
; __global__ void __launch_bounds__(512, 2) mega(Params p) {
;     ...
;     GSYNC();
;     for (int rp = 0; rp < REP_P4; ++rp)
;     for (int item = bid; item < 256; item += nb) {
;       const int pl = item & 7, rest = item >> 3;
;       const int qt = rest & 7, pg = rest >> 3;
;       const int pair = pg * 8 + pl;
;       const int b = pair >> 2, hd = pair & 3;
;       AttArgs a{};
;       a.q = G_XQ + (size_t)b * SEQ * 512 + hd * 128; a.ldq = 512;
;       a.k = G_MEMKV + (size_t)b * 256 * 1024 + hd * 128; a.ldk = 1024;
;       a.v = G_MEMKV + (size_t)b * 256 * 1024 + 512 + hd * 128; a.ldv = 1024;
;       a.o = G_XO + (size_t)b * SEQ * 512 + hd * 128; a.ldo = 512;
;       a.scale = 0.08838834764831845f;
;       attn_item<128, 128, 0, 1>(a, qt * 256, 0, 4);
.LBB0_1071:
	s_or_b64 exec, exec, s[4:5]
.LBB0_1072:
	s_or_b64 exec, exec, s[0:1]
	v_readlane_b32 s0, v253, 38
	v_readlane_b32 s1, v253, 39
	s_andn2_b64 vcc, exec, s[0:1]
	v_readlane_b32 s14, v252, 0
	s_waitcnt lgkmcnt(0)
	s_barrier
	s_cbranch_vccz .LBB0_1077

; #define GSYNC() do { for (int _r = 0; _r < REP_SYNC; ++_r) xcd_barrier(xbar); } while (0)
; DI unsigned xb_ld(unsigned* p) { return __hip_atomic_load(p, __ATOMIC_RELAXED, __HIP_MEMORY_SCOPE_AGENT); }
; DI unsigned xb_add(unsigned* p, unsigned v) { return __hip_atomic_fetch_add(p, v, __ATOMIC_RELAXED, __HIP_MEMORY_SCOPE_AGENT); }
; #define XB_SPIN(cond, bar) do { unsigned _sp = 0; while (cond) { __builtin_amdgcn_s_sleep(1); \
;     if ((++_sp & 255u) == 0u) { if (xb_ld(&(bar)[XB_TMO])) break; if (_sp > XB_SPIN_CAP) { atomicAdd(&(bar)[XB_TMO], 1u); break; } } } } while (0)
; #define G_XF (outp())
; #define G_SS ((float*)(wsp() + OFF_SS))
; DI void xcd_barrier(const XcdBarrier& b) {
;     ...
;       xb_add(&bar[XB_XGEN(b.x)], 1u);
;       asm volatile("s_waitcnt vmcnt(0)" ::: "memory");
;     } else {
;       XB_SPIN(xb_ld(&bar[XB_XGEN(b.x)]) == gen, bar);
;       __builtin_amdgcn_fence(__ATOMIC_ACQUIRE, "agent");
;       asm volatile("s_waitcnt vmcnt(0)" ::: "memory");
;     }
;   }
;   __syncthreads();
; __global__ void __launch_bounds__(512, 2) mega(Params p) {
;     ...
;     GSYNC();
;     for (int item = bid; item < 4 * 64; item += nb) {
;       const int nt = item >> 6, mt = item & 63;
;       e.ss = nullptr; e.xf = G_XF; e.xb = G_XB; e.ss_out = G_SS;
;       gemm_tile<EPI_RESID, 256, false>(G_XO, 512, wb + W_XO, 512, mt * 256, nt * 256, e);
.LBB0_1145:
	s_or_b64 exec, exec, s[4:5]
.LBB0_1146:
	s_or_b64 exec, exec, s[0:1]
	v_readlane_b32 s0, v253, 38
	v_readlane_b32 s1, v253, 39
	s_and_b64 vcc, exec, s[0:1]
	s_waitcnt lgkmcnt(0)
	s_barrier
	s_cbranch_vccz .LBB0_1189
	v_readlane_b32 s0, v254, 44
	s_add_u32 s14, s0, 0x9a0000
	v_readlane_b32 s0, v254, 45
	s_addc_u32 s15, s0, 0
	v_readlane_b32 s0, v254, 42
	v_readlane_b32 s2, v254, 48
	v_readlane_b32 s1, v254, 43
	s_add_u32 s4, s0, s2
	s_addc_u32 s5, s1, 0
	v_readlane_b32 s20, v254, 19
	v_readlane_b32 s21, v254, 17
	v_readlane_b32 s24, v252, 0
	s_branch .LBB0_1149

; #define GSYNC() do { for (int _r = 0; _r < REP_SYNC; ++_r) xcd_barrier(xbar); } while (0)
; DI unsigned xb_ld(unsigned* p) { return __hip_atomic_load(p, __ATOMIC_RELAXED, __HIP_MEMORY_SCOPE_AGENT); }
; DI unsigned xb_add(unsigned* p, unsigned v) { return __hip_atomic_fetch_add(p, v, __ATOMIC_RELAXED, __HIP_MEMORY_SCOPE_AGENT); }
; #define XB_SPIN(cond, bar) do { unsigned _sp = 0; while (cond) { __builtin_amdgcn_s_sleep(1); \
;     if ((++_sp & 255u) == 0u) { if (xb_ld(&(bar)[XB_TMO])) break; if (_sp > XB_SPIN_CAP) { atomicAdd(&(bar)[XB_TMO], 1u); break; } } } } while (0)
; #define G_SS ((float*)(wsp() + OFF_SS))
; DI void xcd_barrier(const XcdBarrier& b) {
;     ...
;       xb_add(&bar[XB_XGEN(b.x)], 1u);
;       asm volatile("s_waitcnt vmcnt(0)" ::: "memory");
;     } else {
;       XB_SPIN(xb_ld(&bar[XB_XGEN(b.x)]) == gen, bar);
;       __builtin_amdgcn_fence(__ATOMIC_ACQUIRE, "agent");
;       asm volatile("s_waitcnt vmcnt(0)" ::: "memory");
;     }
;   }
;   __syncthreads();
; __global__ void __launch_bounds__(512, 2) mega(Params p) {
;     ...
;     GSYNC();
;     bool pre7 = false;
;     for (int rp = 0; rp < REP_P7; ++rp)
;     for (int item = bid; item < 20 * 64 + 4 * 64; item += nb) {
;       e.ss = G_SS; e.nss = 16; e.inv_n = 1.f / 1024.f; e.out = G_ACT; e.ldo = 2816;
;       if (item < 1280) {
;         const int nt = item >> 6, mt = item & 63;
;         const int nxt = item + nb;
;         const bool chain = nxt < 1280;
;         gemm_tile256<EPI_GU, true>(G_XB, DM, wb + W_GU, DM, mt * 256, nt * 256, e, pre7, chain ? (nxt & 63) * 256 : -1, (nxt >> 6) * 256);
.LBB0_1240:
	s_or_b64 exec, exec, s[4:5]
.LBB0_1241:
	s_or_b64 exec, exec, s[0:1]
	v_readlane_b32 s0, v253, 42
	v_readlane_b32 s1, v253, 43
	s_andn2_b64 vcc, exec, s[0:1]
	s_waitcnt lgkmcnt(0)
	s_barrier
	s_cbranch_vccnz .LBB0_1267
	v_readlane_b32 s0, v254, 44
	s_add_u32 s4, s0, 0xaa0000
	v_readlane_b32 s0, v254, 45
	s_addc_u32 s5, s0, 0
	v_readlane_b32 s0, v254, 42
	v_readlane_b32 s2, v254, 48
	v_readlane_b32 s1, v254, 43
	s_add_u32 s6, s0, s2
	s_addc_u32 s7, s1, 0
	s_mov_b64 s[8:9], 0
	v_readlane_b32 s20, v254, 17
	v_readlane_b32 s21, v254, 21
	v_readlane_b32 s24, v254, 19
	v_readlane_b32 s25, v252, 0
	s_branch .LBB0_1245

; #define GSYNC() do { for (int _r = 0; _r < REP_SYNC; ++_r) xcd_barrier(xbar); } while (0)
; DI unsigned xb_ld(unsigned* p) { return __hip_atomic_load(p, __ATOMIC_RELAXED, __HIP_MEMORY_SCOPE_AGENT); }
; DI unsigned xb_add(unsigned* p, unsigned v) { return __hip_atomic_fetch_add(p, v, __ATOMIC_RELAXED, __HIP_MEMORY_SCOPE_AGENT); }
; #define XB_SPIN(cond, bar) do { unsigned _sp = 0; while (cond) { __builtin_amdgcn_s_sleep(1); \
;     if ((++_sp & 255u) == 0u) { if (xb_ld(&(bar)[XB_TMO])) break; if (_sp > XB_SPIN_CAP) { atomicAdd(&(bar)[XB_TMO], 1u); break; } } } } while (0)
; #define G_XF (outp())
; #define G_SS ((float*)(wsp() + OFF_SS))
; DI void xcd_barrier(const XcdBarrier& b) {
;     ...
;       xb_add(&bar[XB_XGEN(b.x)], 1u);
;       asm volatile("s_waitcnt vmcnt(0)" ::: "memory");
;     } else {
;       XB_SPIN(xb_ld(&bar[XB_XGEN(b.x)]) == gen, bar);
;       __builtin_amdgcn_fence(__ATOMIC_ACQUIRE, "agent");
;       asm volatile("s_waitcnt vmcnt(0)" ::: "memory");
;     }
;   }
;   __syncthreads();
; __global__ void __launch_bounds__(512, 2) mega(Params p) {
;     ...
;     GSYNC();
;     for (int item = bid; item < 4 * 64; item += nb) {
;       const int nt = item >> 6, mt = item & 63;
;       e.ss = nullptr; e.xf = G_XF; e.xb = G_XB; e.ss_out = G_SS;
;       gemm_tile<EPI_RESID, 256, false>(G_ACT, 2816, wb + W_DOWN, 2816, mt * 256, nt * 256, e);
.LBB0_1318:
	s_or_b64 exec, exec, s[4:5]
.LBB0_1319:
	s_or_b64 exec, exec, s[0:1]
	v_readlane_b32 s0, v253, 38
	v_readlane_b32 s1, v253, 39
	s_and_b64 vcc, exec, s[0:1]
	s_waitcnt lgkmcnt(0)
	s_barrier
	s_cbranch_vccz .LBB0_1362
	v_readlane_b32 s0, v254, 44
	s_add_u32 s14, s0, 0x15a0000
	v_readlane_b32 s0, v254, 45
	s_addc_u32 s15, s0, 0
	v_readlane_b32 s0, v254, 42
	v_readlane_b32 s2, v254, 48
	v_readlane_b32 s1, v254, 43
	s_add_u32 s4, s0, s2
	s_addc_u32 s5, s1, 0
	v_readlane_b32 s20, v254, 19
	v_readlane_b32 s21, v254, 17
	v_readlane_b32 s24, v252, 0
	s_branch .LBB0_1322

; DI unsigned xb_ld(unsigned* p) { return __hip_atomic_load(p, __ATOMIC_RELAXED, __HIP_MEMORY_SCOPE_AGENT); }
; DI unsigned xb_add(unsigned* p, unsigned v) { return __hip_atomic_fetch_add(p, v, __ATOMIC_RELAXED, __HIP_MEMORY_SCOPE_AGENT); }
; #define XB_SPIN(cond, bar) do { unsigned _sp = 0; while (cond) { __builtin_amdgcn_s_sleep(1); \
;     if ((++_sp & 255u) == 0u) { if (xb_ld(&(bar)[XB_TMO])) break; if (_sp > XB_SPIN_CAP) { atomicAdd(&(bar)[XB_TMO], 1u); break; } } } } while (0)
; DI void xcd_barrier(const XcdBarrier& b) {
;     ...
;       const unsigned og = xb_add(&bar[XB_TOP], 1u);
;       const unsigned tg = og / nx;
;       if (og + 1u == (tg + 1u) * nx) xb_add(&bar[XB_TOPGEN], 1u);
;       else XB_SPIN(xb_ld(&bar[XB_TOPGEN]) == tg, bar);
;       __builtin_amdgcn_fence(__ATOMIC_ACQUIRE, "agent");
;       xb_add(&bar[XB_XGEN(b.x)], 1u);
;       asm volatile("s_waitcnt vmcnt(0)" ::: "memory");
.LBB0_1411:
	s_or_b64 exec, exec, s[2:3]
	s_mov_b64 s[2:3], exec
	v_mbcnt_lo_u32_b32 v0, s2, 0
	v_mbcnt_hi_u32_b32 v0, s3, v0
	v_cmp_eq_u32_e32 vcc, 0, v0
	s_and_saveexec_b64 s[4:5], vcc
	s_cbranch_execnz .LBB0_1412
	s_getpc_b64 s[98:99]
